# S1 issues its first LDS fragment reads right after the barrier; bf16 packs of tile i deferred into the LDS-latency window of the next QK segment
# speedup vs baseline: 1.0488x; 1.0074x over previous
.LBB0_963:
	s_or_b64 exec, exec, s[12:13]
	s_waitcnt lgkmcnt(0)
	v_add_u32_e32 v234, s46, v154
	ds_read_b128 v[218:221], v234 offset:43232
	ds_read_b128 v[222:225], v234 offset:43200
	ds_read_b128 v[226:229], v234 offset:43168
	ds_read_b128 v[230:233], v234 offset:43136
	s_waitcnt lgkmcnt(0)
	s_waitcnt lgkmcnt(3)
	v_pk_mul_f32 v[12:13], v[12:13], v[218:219]
	s_waitcnt lgkmcnt(2)
	v_pk_mul_f32 v[8:9], v[8:9], v[222:223]
	s_waitcnt lgkmcnt(1)
	v_pk_mul_f32 v[4:5], v[4:5], v[226:227]
	v_pk_mul_f32 v[14:15], v[14:15], v[220:221]
	v_pk_mul_f32 v[10:11], v[10:11], v[224:225]
	v_pk_mul_f32 v[6:7], v[6:7], v[228:229]
	s_waitcnt lgkmcnt(0)
	v_pk_mul_f32 v[2:3], v[2:3], v[232:233]
	v_pk_mul_f32 v[0:1], v[0:1], v[230:231]
	v_pk_mul_f32 v[28:29], v[28:29], v[218:219]
	v_pk_mul_f32 v[24:25], v[24:25], v[222:223]
	v_pk_mul_f32 v[20:21], v[20:21], v[226:227]
	v_pk_mul_f32 v[30:31], v[30:31], v[220:221]
	v_pk_mul_f32 v[26:27], v[26:27], v[224:225]
	v_pk_mul_f32 v[22:23], v[22:23], v[228:229]
	v_pk_mul_f32 v[18:19], v[18:19], v[232:233]
	v_pk_mul_f32 v[16:17], v[16:17], v[230:231]
	v_mov_b32_e32 v235, 1.0

; #define SLOAD(j) do { const size_t krow = (size_t)(seq0 + key0 + 64 * (j) + sr); kst = *(const bf16x8*)(Kp + krow * ldk + sc); vstg = *(const bf16x8*)(Vp + krow * ldk + sc); \
;         if (MODE == 2) { if (tid < 256) pst = *(const bf16x8*)(Kpe + (size_t)(seq0 + key0 + 64 * (j) + pr) * 32 + pc); } } while (0)
; #define SLOAD(S, j) do { const size_t krow = (size_t)(seq0 + 64 * (j) + sr); ks##S = *(const bf16x8*)(Kp + krow * 1024 + sc); vs##S = *(const bf16x8*)(Vp + krow * 1024 + sc); \
;         ps##S = *(const bf16x8*)(Kpe + (size_t)(seq0 + 64 * (j) + pr) * 32 + pc); } while (0)
; #define SBAR() __builtin_amdgcn_sched_barrier(0)
; #define SLOAD(S, t) do { const int t_ = (t); if (t_ + 1 < NT) { ks##S = *(const bf16x8*)(Kth + (size_t)(t_ + 1) * 65536); ps##S = *(const bf16x8*)(Pth + (size_t)(t_ + 1) * 2048); } \
;         if (t_ < NT) { vs##S = *(const bf16x8*)(Vth + (size_t)t_ * 65536); } } while (0)
; #define SBAR() __builtin_amdgcn_sched_barrier(0)
; __device__ __forceinline__ void mla_softmax_rel_kp(f32x16& p0, f32x16& p1, f32x16& negm, bool first, float& l_reg, float& alpha, bf16x8& pa0, bf16x8& pa1, bf16x8& pa2, bf16x8& pa3) {
;     ...
;     { auto rr = __builtin_amdgcn_permlane32_swap(__float_as_uint(ps), __float_as_uint(ps), false, false); ps = __uint_as_float(rr[0]) + __uint_as_float(rr[1]); }
;     l_reg = l_reg * alpha + ps;
;     pa0 = pack8(p0, 0); pa1 = pack8(p0, 8); pa2 = pack8(p1, 0); pa3 = pack8(p1, 8);
; __device__ __forceinline__ void mla_unit2(const Params& P, unsigned char* lds, int h, int rb, int grp, bool dry = false) {
;     ...
;         SLOAD(O, i + 1 + hoff); SBAR();
;         mla_qkt_neg(p0, p1, negm, K0, qr, r32, hi);
.Lmla_nobar7:
	s_add_u32 s60, s60, 0x20000
	s_addc_u32 s61, s61, 0
	s_add_u32 s62, s62, 0x20000
	s_addc_u32 s63, s63, 0
	s_add_u32 s64, s64, 0x1000
	s_addc_u32 s65, s65, 0
	s_cmp_lt_u32 s41, s54
	s_cbranch_scc0 .Lmla_exit_pack
	ds_read_b128 v[80:83], v157
	ds_read_b128 v[146:149], v157 offset:32
	ds_read_b128 v[150:153], v157 offset:6656
	ds_read_b128 v[168:171], v157 offset:6688
	v_cvt_pk_bf16_f32 v55, v54, v55
	v_cvt_pk_bf16_f32 v54, v52, v53
	v_cvt_pk_bf16_f32 v52, v48, v49
	v_cvt_pk_bf16_f32 v53, v50, v51
	v_cvt_pk_bf16_f32 v48, v56, v57
	v_cvt_pk_bf16_f32 v49, v58, v59
	v_cvt_pk_bf16_f32 v50, v60, v61
	v_cvt_pk_bf16_f32 v51, v62, v63
	v_cvt_pk_bf16_f32 v60, v64, v65
	v_cvt_pk_bf16_f32 v61, v66, v67
	v_cvt_pk_bf16_f32 v62, v68, v69
	v_cvt_pk_bf16_f32 v63, v70, v71
	v_cvt_pk_bf16_f32 v56, v72, v73
	v_cvt_pk_bf16_f32 v57, v74, v75
	v_cvt_pk_bf16_f32 v58, v76, v77
	v_cvt_pk_bf16_f32 v59, v78, v79
	s_branch .Lmla_s1e_body
.LBB0_965:
	ds_read_b128 v[80:83], v157
	ds_read_b128 v[146:149], v157 offset:32
	ds_read_b128 v[150:153], v157 offset:6656
	ds_read_b128 v[168:171], v157 offset:6688
.Lmla_s1e_body:
	s_add_i32 s47, s40, s41
	s_add_i32 s4, s47, 2
	s_cmp_lt_i32 s4, s54
	s_cselect_b64 s[44:45], -1, 0
	s_cmp_ge_i32 s4, s54
	s_cbranch_scc1 .LBB0_967
	global_load_dwordx4 v[136:139], v166, s[60:61]
	global_load_dwordx4 v[140:143], v167, s[64:65]

; #define HBAR() do { asm volatile("s_waitcnt lgkmcnt(0)" ::: "memory"); __builtin_amdgcn_s_barrier(); asm volatile("" ::: "memory"); } while (0)
; __device__ __forceinline__ void mla_unit2(const Params& P, unsigned char* lds, int h, int rb, int grp, bool dry = false) {
;     ...
;         mla_qkt_neg(p0, p1, negm, K0, qr, r32, hi);
;         if (i > 0) { pv_both_kp(o[0], o[1], vb0 + A_VBUF, pa0, pa1, pa2, pa3); }
;         HBAR();
.LBB0_969:
	s_waitcnt lgkmcnt(3)
	v_mfma_f32_32x32x16_bf16 v[64:79], v[80:83], v[96:99], v[32:47]
	s_waitcnt lgkmcnt(1)
	v_mfma_f32_32x32x16_bf16 v[80:95], v[150:153], v[96:99], v[32:47]
	v_mfma_f32_32x32x16_bf16 v[64:79], v[146:149], v[100:103], v[64:79]
	ds_read_b128 v[146:149], v157 offset:64
	ds_read_b128 v[150:153], v157 offset:96
	s_waitcnt lgkmcnt(2)
	v_mfma_f32_32x32x16_bf16 v[80:95], v[168:171], v[100:103], v[80:95]
	s_waitcnt lgkmcnt(1)
	v_mfma_f32_32x32x16_bf16 v[64:79], v[146:149], v[104:107], v[64:79]
	ds_read_b128 v[146:149], v157 offset:6720
	ds_read_b128 v[168:171], v157 offset:6752
	s_waitcnt lgkmcnt(1)
	v_mfma_f32_32x32x16_bf16 v[80:95], v[146:149], v[104:107], v[80:95]
	v_mfma_f32_32x32x16_bf16 v[64:79], v[150:153], v[108:111], v[64:79]
	ds_read_b128 v[146:149], v157 offset:128
	ds_read_b128 v[150:153], v157 offset:160
	s_waitcnt lgkmcnt(2)
	v_mfma_f32_32x32x16_bf16 v[80:95], v[168:171], v[108:111], v[80:95]
	s_waitcnt lgkmcnt(1)
	v_mfma_f32_32x32x16_bf16 v[64:79], v[146:149], v[112:115], v[64:79]
	ds_read_b128 v[146:149], v157 offset:6784
	ds_read_b128 v[168:171], v157 offset:6816
	ds_read_b64_tr_b16 v[182:183], v204 offset:0
	ds_read_b64_tr_b16 v[184:185], v204 offset:0x100
	s_waitcnt lgkmcnt(1)
	v_mfma_f32_32x32x16_bf16 v[80:95], v[146:149], v[112:115], v[80:95]
	ds_read_b64_tr_b16 v[146:147], v204 offset:0x800
	ds_read_b64_tr_b16 v[148:149], v204 offset:0x900
	ds_read_b64_tr_b16 v[186:187], v204 offset:0x1000
	ds_read_b64_tr_b16 v[188:189], v204 offset:0x1100
	ds_read_b64_tr_b16 v[190:191], v204 offset:0x1800
	ds_read_b64_tr_b16 v[192:193], v204 offset:0x1900
	ds_read_b64_tr_b16 v[206:207], v204 offset:0x200
	ds_read_b64_tr_b16 v[208:209], v204 offset:0x300
	v_mfma_f32_32x32x16_bf16 v[64:79], v[150:153], v[116:119], v[64:79]
	ds_read_b64_tr_b16 v[150:151], v204 offset:0xa00
	ds_read_b64_tr_b16 v[152:153], v204 offset:0xb00
	ds_read_b64_tr_b16 v[210:211], v204 offset:0x1200
	ds_read_b64_tr_b16 v[212:213], v204 offset:0x1300
	ds_read_b64_tr_b16 v[214:215], v204 offset:0x1a00
	ds_read_b64_tr_b16 v[216:217], v204 offset:0x1b00
	s_waitcnt lgkmcnt(8)
	s_waitcnt lgkmcnt(0)
	v_mfma_f32_32x32x16_bf16 v[80:95], v[168:171], v[116:119], v[80:95]
	v_mfma_f32_32x32x16_bf16 v[0:15], v[60:63], v[182:185], v[0:15]
	s_waitcnt lgkmcnt(0)
	v_mfma_f32_32x32x16_bf16 v[0:15], v[56:59], v[146:149], v[0:15]
	v_mfma_f32_32x32x16_bf16 v[0:15], v[52:55], v[186:189], v[0:15]
	v_mfma_f32_32x32x16_bf16 v[0:15], v[48:51], v[190:193], v[0:15]
	v_mfma_f32_32x32x16_bf16 v[16:31], v[60:63], v[206:209], v[16:31]
	s_waitcnt lgkmcnt(0)
	s_cmp_lg_u32 s40, 0
	s_cbranch_scc0 .Lmla_nobar4
	s_barrier

; __device__ __forceinline__ void mla_softmax_rel_kp(f32x16& p0, f32x16& p1, f32x16& negm, bool first, float& l_reg, float& alpha, bf16x8& pa0, bf16x8& pa1, bf16x8& pa2, bf16x8& pa3) {
;     ...
; #pragma unroll
;     for (int r = 0; r < 16; ++r) { p0[r] = __builtin_amdgcn_exp2f(p0[r]); p1[r] = __builtin_amdgcn_exp2f(p1[r]); }
;     float ps = 0.f;
; #pragma unroll
;     for (int r = 0; r < 16; ++r) ps += p0[r];
; #pragma unroll
;     for (int r = 0; r < 16; ++r) ps += p1[r];
;     { auto rr = __builtin_amdgcn_permlane32_swap(__float_as_uint(ps), __float_as_uint(ps), false, false); ps = __uint_as_float(rr[0]) + __uint_as_float(rr[1]); }
;     l_reg = l_reg * alpha + ps;
.LBB0_977:
	v_exp_f32_e32 v64, v64
	v_exp_f32_e32 v65, v65
	v_exp_f32_e32 v66, v66
	v_add_f32_e32 v236, v64, v236
	v_exp_f32_e32 v67, v67
	v_add_f32_e32 v237, v65, v237
	v_exp_f32_e32 v68, v68
	v_add_f32_e32 v236, v66, v236
	v_exp_f32_e32 v69, v69
	v_add_f32_e32 v237, v67, v237
	v_exp_f32_e32 v70, v70
	v_add_f32_e32 v236, v68, v236
	v_exp_f32_e32 v71, v71
	v_add_f32_e32 v237, v69, v237
	v_exp_f32_e32 v72, v72
	v_add_f32_e32 v236, v70, v236
	v_exp_f32_e32 v73, v73
	v_add_f32_e32 v237, v71, v237
	v_exp_f32_e32 v74, v74
	v_add_f32_e32 v236, v72, v236
	v_exp_f32_e32 v75, v75
	v_add_f32_e32 v237, v73, v237
	v_exp_f32_e32 v76, v76
	v_add_f32_e32 v236, v74, v236
	v_exp_f32_e32 v77, v77
	v_add_f32_e32 v237, v75, v237
	v_exp_f32_e32 v78, v78
	v_add_f32_e32 v236, v76, v236
	v_exp_f32_e32 v79, v79
	v_add_f32_e32 v237, v77, v237
	v_exp_f32_e32 v80, v80
	v_add_f32_e32 v236, v78, v236
	v_exp_f32_e32 v81, v81
	v_add_f32_e32 v237, v79, v237
	v_exp_f32_e32 v82, v82
	v_add_f32_e32 v236, v80, v236
	v_exp_f32_e32 v83, v83
	v_add_f32_e32 v237, v81, v237
	v_exp_f32_e32 v84, v84
	v_add_f32_e32 v236, v82, v236
	v_exp_f32_e32 v85, v85
	v_add_f32_e32 v237, v83, v237
	v_exp_f32_e32 v86, v86
	v_add_f32_e32 v236, v84, v236
	v_exp_f32_e32 v87, v87
	v_add_f32_e32 v237, v85, v237
	v_exp_f32_e32 v88, v88
	v_add_f32_e32 v236, v86, v236
	v_exp_f32_e32 v89, v89
	v_add_f32_e32 v237, v87, v237
	v_exp_f32_e32 v90, v90
	v_add_f32_e32 v236, v88, v236
	v_exp_f32_e32 v91, v91
	v_add_f32_e32 v237, v89, v237
	v_exp_f32_e32 v92, v92
	v_add_f32_e32 v236, v90, v236
	v_exp_f32_e32 v93, v93
	v_add_f32_e32 v237, v91, v237
	v_exp_f32_e32 v94, v94
	v_add_f32_e32 v236, v92, v236
	v_exp_f32_e32 v95, v95
	v_add_f32_e32 v237, v93, v237
	v_add_f32_e32 v236, v94, v236
	v_add_f32_e32 v237, v95, v237
	v_cmp_gt_f32_e32 vcc, 1.0, v144
	s_cbranch_vccz .LBB0_981
	s_and_saveexec_b64 s[12:13], s[10:11]
	ds_write_b32 v202, v144 offset:43136
	s_or_b64 exec, exec, s[12:13]
	s_waitcnt lgkmcnt(0)
	v_add_u32_e32 v234, s46, v154
	ds_read_b128 v[218:221], v234 offset:43232
	ds_read_b128 v[222:225], v234 offset:43200
	ds_read_b128 v[226:229], v234 offset:43168
	ds_read_b128 v[230:233], v234 offset:43136
	s_waitcnt lgkmcnt(0)
	s_waitcnt lgkmcnt(3)
	v_pk_mul_f32 v[12:13], v[12:13], v[218:219]
	s_waitcnt lgkmcnt(2)
	v_pk_mul_f32 v[8:9], v[8:9], v[222:223]
	s_waitcnt lgkmcnt(1)
	v_pk_mul_f32 v[4:5], v[4:5], v[226:227]
	v_pk_mul_f32 v[14:15], v[14:15], v[220:221]
	v_pk_mul_f32 v[10:11], v[10:11], v[224:225]
	v_pk_mul_f32 v[6:7], v[6:7], v[228:229]
	s_waitcnt lgkmcnt(0)
	v_pk_mul_f32 v[2:3], v[2:3], v[232:233]
	v_pk_mul_f32 v[0:1], v[0:1], v[230:231]
	v_pk_mul_f32 v[28:29], v[28:29], v[218:219]
	v_pk_mul_f32 v[24:25], v[24:25], v[222:223]
	v_pk_mul_f32 v[20:21], v[20:21], v[226:227]
	v_pk_mul_f32 v[30:31], v[30:31], v[220:221]
	v_pk_mul_f32 v[26:27], v[26:27], v[224:225]
	v_pk_mul_f32 v[22:23], v[22:23], v[228:229]
	v_pk_mul_f32 v[18:19], v[18:19], v[232:233]
	v_pk_mul_f32 v[16:17], v[16:17], v[230:231]
	v_mov_b32_e32 v144, 1.0

; #define SLOAD(j) do { const size_t krow = (size_t)(seq0 + key0 + 64 * (j) + sr); kst = *(const bf16x8*)(Kp + krow * ldk + sc); vstg = *(const bf16x8*)(Vp + krow * ldk + sc); \
;         if (MODE == 2) { if (tid < 256) pst = *(const bf16x8*)(Kpe + (size_t)(seq0 + key0 + 64 * (j) + pr) * 32 + pc); } } while (0)
; #define SLOAD(S, j) do { const size_t krow = (size_t)(seq0 + 64 * (j) + sr); ks##S = *(const bf16x8*)(Kp + krow * 1024 + sc); vs##S = *(const bf16x8*)(Vp + krow * 1024 + sc); \
;         ps##S = *(const bf16x8*)(Kpe + (size_t)(seq0 + 64 * (j) + pr) * 32 + pc); } while (0)
; #define SBAR() __builtin_amdgcn_sched_barrier(0)
; #define SLOAD(S, t) do { const int t_ = (t); if (t_ + 1 < NT) { ks##S = *(const bf16x8*)(Kth + (size_t)(t_ + 1) * 65536); ps##S = *(const bf16x8*)(Pth + (size_t)(t_ + 1) * 2048); } \
;         if (t_ < NT) { vs##S = *(const bf16x8*)(Vth + (size_t)t_ * 65536); } } while (0)
; #define HBAR() do { asm volatile("s_waitcnt lgkmcnt(0)" ::: "memory"); __builtin_amdgcn_s_barrier(); asm volatile("" ::: "memory"); } while (0)
; #define SBAR() __builtin_amdgcn_sched_barrier(0)
; __device__ __forceinline__ void mla_softmax_rel_kp(f32x16& p0, f32x16& p1, f32x16& negm, bool first, float& l_reg, float& alpha, bf16x8& pa0, bf16x8& pa1, bf16x8& pa2, bf16x8& pa3) {
;     ...
;     { auto rr = __builtin_amdgcn_permlane32_swap(__float_as_uint(ps), __float_as_uint(ps), false, false); ps = __uint_as_float(rr[0]) + __uint_as_float(rr[1]); }
;     l_reg = l_reg * alpha + ps;
;     pa0 = pack8(p0, 0); pa1 = pack8(p0, 8); pa2 = pack8(p1, 0); pa3 = pack8(p1, 8);
; __device__ __forceinline__ void mla_unit2(const Params& P, unsigned char* lds, int h, int rb, int grp, bool dry = false) {
;     ...
;         HBAR();
;         SLOAD(E, i + 2 + hoff); SBAR();
;         mla_qkt_neg(p0, p1, negm, K1, qr, r32, hi);
.Lmla_nobar5:
	ds_read_b128 v[146:149], v157 offset:13312
	ds_read_b128 v[150:153], v157 offset:13344
	v_cvt_pk_bf16_f32 v87, v86, v87
	v_cvt_pk_bf16_f32 v86, v84, v85
	v_cvt_pk_bf16_f32 v85, v82, v83
	v_cvt_pk_bf16_f32 v84, v80, v81
	v_cvt_pk_bf16_f32 v82, v92, v93
	v_cvt_pk_bf16_f32 v83, v94, v95
	v_cvt_pk_bf16_f32 v80, v88, v89
	v_cvt_pk_bf16_f32 v81, v90, v91
	v_cvt_pk_bf16_f32 v92, v64, v65
	v_cvt_pk_bf16_f32 v93, v66, v67
	v_cvt_pk_bf16_f32 v94, v68, v69
	v_cvt_pk_bf16_f32 v95, v70, v71
	v_cvt_pk_bf16_f32 v88, v72, v73
	v_cvt_pk_bf16_f32 v89, v74, v75
	v_cvt_pk_bf16_f32 v90, v76, v77
	v_cvt_pk_bf16_f32 v91, v78, v79
	s_add_u32 s60, s60, 0x20000
	s_addc_u32 s61, s61, 0
	s_add_u32 s62, s62, 0x20000
	s_addc_u32 s63, s63, 0
	s_add_u32 s64, s64, 0x1000
	s_addc_u32 s65, s65, 0
	s_add_i32 s47, s47, 3
	s_cmp_ge_i32 s47, s54
	s_cbranch_scc1 .LBB0_983
	global_load_dwordx4 v[120:123], v166, s[60:61]
	global_load_dwordx4 v[124:127], v167, s[64:65]

; #define HBAR() do { asm volatile("s_waitcnt lgkmcnt(0)" ::: "memory"); __builtin_amdgcn_s_barrier(); asm volatile("" ::: "memory"); } while (0)
; __device__ __forceinline__ void mla_unit2(const Params& P, unsigned char* lds, int h, int rb, int grp, bool dry = false) {
;     ...
;         mla_qkt_neg(p0, p1, negm, K1, qr, r32, hi);
;         pv_both_kp(o[0], o[1], vb0, pa0, pa1, pa2, pa3);
;         HBAR();
.LBB0_985:
	s_waitcnt lgkmcnt(1)
	v_mfma_f32_32x32x16_bf16 v[64:79], v[146:149], v[96:99], v[32:47]
	ds_read_b128 v[146:149], v157 offset:19968
	ds_read_b128 v[162:165], v157 offset:20000
	s_waitcnt lgkmcnt(1)
	v_mfma_f32_32x32x16_bf16 v[48:63], v[146:149], v[96:99], v[32:47]
	v_mfma_f32_32x32x16_bf16 v[64:79], v[150:153], v[100:103], v[64:79]
	ds_read_b128 v[146:149], v157 offset:13376
	ds_read_b128 v[150:153], v157 offset:13408
	s_waitcnt lgkmcnt(2)
	v_mfma_f32_32x32x16_bf16 v[48:63], v[162:165], v[100:103], v[48:63]
	s_waitcnt lgkmcnt(1)
	v_mfma_f32_32x32x16_bf16 v[64:79], v[146:149], v[104:107], v[64:79]
	ds_read_b128 v[146:149], v157 offset:20032
	ds_read_b128 v[162:165], v157 offset:20064
	s_waitcnt lgkmcnt(1)
	v_mfma_f32_32x32x16_bf16 v[48:63], v[146:149], v[104:107], v[48:63]
	v_mfma_f32_32x32x16_bf16 v[64:79], v[150:153], v[108:111], v[64:79]
	ds_read_b128 v[146:149], v157 offset:13440
	ds_read_b128 v[150:153], v157 offset:13472
	s_waitcnt lgkmcnt(2)
	v_mfma_f32_32x32x16_bf16 v[48:63], v[162:165], v[108:111], v[48:63]
	s_waitcnt lgkmcnt(1)
	v_mfma_f32_32x32x16_bf16 v[64:79], v[146:149], v[112:115], v[64:79]
	ds_read_b128 v[146:149], v157 offset:20096
	ds_read_b128 v[162:165], v157 offset:20128
	ds_read_b64_tr_b16 v[168:169], v199 offset:0
	ds_read_b64_tr_b16 v[170:171], v199 offset:0x100
	s_waitcnt lgkmcnt(1)
	v_mfma_f32_32x32x16_bf16 v[48:63], v[146:149], v[112:115], v[48:63]
	ds_read_b64_tr_b16 v[146:147], v199 offset:0x800
	ds_read_b64_tr_b16 v[148:149], v199 offset:0x900
	ds_read_b64_tr_b16 v[182:183], v199 offset:0x1000
	ds_read_b64_tr_b16 v[184:185], v199 offset:0x1100
	ds_read_b64_tr_b16 v[186:187], v199 offset:0x1800
	ds_read_b64_tr_b16 v[188:189], v199 offset:0x1900
	ds_read_b64_tr_b16 v[190:191], v199 offset:0x200
	ds_read_b64_tr_b16 v[192:193], v199 offset:0x300
	v_mfma_f32_32x32x16_bf16 v[64:79], v[150:153], v[116:119], v[64:79]
	ds_read_b64_tr_b16 v[150:151], v199 offset:0xa00
	ds_read_b64_tr_b16 v[152:153], v199 offset:0xb00
	ds_read_b64_tr_b16 v[208:209], v199 offset:0x1200
	ds_read_b64_tr_b16 v[210:211], v199 offset:0x1300
	ds_read_b64_tr_b16 v[212:213], v199 offset:0x1a00
	ds_read_b64_tr_b16 v[214:215], v199 offset:0x1b00
	s_waitcnt lgkmcnt(8)
	s_waitcnt lgkmcnt(0)
	v_mfma_f32_32x32x16_bf16 v[48:63], v[162:165], v[116:119], v[48:63]
	v_mfma_f32_32x32x16_bf16 v[0:15], v[92:95], v[168:171], v[0:15]
	s_waitcnt lgkmcnt(0)
	v_mfma_f32_32x32x16_bf16 v[0:15], v[88:91], v[146:149], v[0:15]
	v_mfma_f32_32x32x16_bf16 v[0:15], v[84:87], v[182:185], v[0:15]
	v_mfma_f32_32x32x16_bf16 v[0:15], v[80:83], v[186:189], v[0:15]
	v_mfma_f32_32x32x16_bf16 v[16:31], v[92:95], v[190:193], v[16:31]
	s_waitcnt lgkmcnt(0)
	s_cmp_lg_u32 s40, 0
	s_cbranch_scc0 .Lmla_nobar6
	s_barrier

; __device__ __forceinline__ void mla_softmax_rel_kp(f32x16& p0, f32x16& p1, f32x16& negm, bool first, float& l_reg, float& alpha, bf16x8& pa0, bf16x8& pa1, bf16x8& pa2, bf16x8& pa3) {
;     ...
; #pragma unroll
;     for (int r = 0; r < 16; ++r) { p0[r] = __builtin_amdgcn_exp2f(p0[r]); p1[r] = __builtin_amdgcn_exp2f(p1[r]); }
;     float ps = 0.f;
; #pragma unroll
;     for (int r = 0; r < 16; ++r) ps += p0[r];
; #pragma unroll
;     for (int r = 0; r < 16; ++r) ps += p1[r];
;     { auto rr = __builtin_amdgcn_permlane32_swap(__float_as_uint(ps), __float_as_uint(ps), false, false); ps = __uint_as_float(rr[0]) + __uint_as_float(rr[1]); }
;     l_reg = l_reg * alpha + ps;
;     pa0 = pack8(p0, 0); pa1 = pack8(p0, 8); pa2 = pack8(p1, 0); pa3 = pack8(p1, 8);
.LBB0_992:
	v_exp_f32_e32 v64, v64
	v_exp_f32_e32 v65, v65
	v_exp_f32_e32 v66, v66
	v_add_f32_e32 v236, v64, v236
	v_exp_f32_e32 v67, v67
	v_add_f32_e32 v237, v65, v237
	v_exp_f32_e32 v68, v68
	v_add_f32_e32 v236, v66, v236
	v_exp_f32_e32 v69, v69
	v_add_f32_e32 v237, v67, v237
	v_exp_f32_e32 v70, v70
	v_add_f32_e32 v236, v68, v236
	v_exp_f32_e32 v71, v71
	v_add_f32_e32 v237, v69, v237
	v_exp_f32_e32 v72, v72
	v_add_f32_e32 v236, v70, v236
	v_exp_f32_e32 v73, v73
	v_add_f32_e32 v237, v71, v237
	v_exp_f32_e32 v74, v74
	v_add_f32_e32 v236, v72, v236
	v_exp_f32_e32 v75, v75
	v_add_f32_e32 v237, v73, v237
	v_exp_f32_e32 v76, v76
	v_add_f32_e32 v236, v74, v236
	v_exp_f32_e32 v77, v77
	v_add_f32_e32 v237, v75, v237
	v_exp_f32_e32 v78, v78
	v_add_f32_e32 v236, v76, v236
	v_exp_f32_e32 v79, v79
	v_add_f32_e32 v237, v77, v237
	v_exp_f32_e32 v48, v48
	v_add_f32_e32 v236, v78, v236
	v_exp_f32_e32 v49, v49
	v_add_f32_e32 v237, v79, v237
	v_exp_f32_e32 v50, v50
	v_add_f32_e32 v236, v48, v236
	v_exp_f32_e32 v51, v51
	v_add_f32_e32 v237, v49, v237
	v_exp_f32_e32 v52, v52
	v_add_f32_e32 v236, v50, v236
	v_exp_f32_e32 v53, v53
	v_add_f32_e32 v237, v51, v237
	v_exp_f32_e32 v54, v54
	v_add_f32_e32 v236, v52, v236
	v_exp_f32_e32 v55, v55
	v_add_f32_e32 v237, v53, v237
	v_exp_f32_e32 v56, v56
	v_add_f32_e32 v236, v54, v236
	v_exp_f32_e32 v57, v57
	v_add_f32_e32 v237, v55, v237
	v_exp_f32_e32 v58, v58
	v_add_f32_e32 v236, v56, v236
	v_exp_f32_e32 v59, v59
	v_add_f32_e32 v237, v57, v237
	v_exp_f32_e32 v60, v60
	v_add_f32_e32 v236, v58, v236
	v_exp_f32_e32 v61, v61
	v_add_f32_e32 v237, v59, v237
	v_exp_f32_e32 v62, v62
	v_add_f32_e32 v236, v60, v236
	v_exp_f32_e32 v63, v63
	v_add_f32_e32 v237, v61, v237
	v_add_f32_e32 v236, v62, v236
	v_add_f32_e32 v237, v63, v237
	v_cmp_gt_f32_e32 vcc, 1.0, v235
	s_cbranch_vccz .LBB0_964
	s_and_saveexec_b64 s[12:13], s[10:11]
	s_cbranch_execz .LBB0_963
	ds_write_b32 v202, v235 offset:43136
	s_branch .LBB0_963

; __device__ __forceinline__ void mla_softmax_rel_kp(f32x16& p0, f32x16& p1, f32x16& negm, bool first, float& l_reg, float& alpha, bf16x8& pa0, bf16x8& pa1, bf16x8& pa2, bf16x8& pa3) {
;     ...
;     { auto rr = __builtin_amdgcn_permlane32_swap(__float_as_uint(ps), __float_as_uint(ps), false, false); ps = __uint_as_float(rr[0]) + __uint_as_float(rr[1]); }
;     l_reg = l_reg * alpha + ps;
;     pa0 = pack8(p0, 0); pa1 = pack8(p0, 8); pa2 = pack8(p1, 0); pa3 = pack8(p1, 8);
; __device__ __forceinline__ void mla_unit2(const Params& P, unsigned char* lds, int h, int rb, int grp, bool dry = false) {
;     ...
;     pv_both_kp(o[0], o[1], vb0 + A_VBUF, pa0, pa1, pa2, pa3);
.Lmla_exit_pack:
	v_cvt_pk_bf16_f32 v55, v54, v55
	v_cvt_pk_bf16_f32 v54, v52, v53
	v_cvt_pk_bf16_f32 v52, v48, v49
	v_cvt_pk_bf16_f32 v53, v50, v51
	v_cvt_pk_bf16_f32 v48, v56, v57
	v_cvt_pk_bf16_f32 v49, v58, v59
	v_cvt_pk_bf16_f32 v50, v60, v61
	v_cvt_pk_bf16_f32 v51, v62, v63
	v_cvt_pk_bf16_f32 v60, v64, v65
	v_cvt_pk_bf16_f32 v61, v66, v67
	v_cvt_pk_bf16_f32 v62, v68, v69
	v_cvt_pk_bf16_f32 v63, v70, v71
	v_cvt_pk_bf16_f32 v56, v72, v73
	v_cvt_pk_bf16_f32 v57, v74, v75
	v_cvt_pk_bf16_f32 v58, v76, v77
	v_cvt_pk_bf16_f32 v59, v78, v79
